# speedup vs baseline: 1.0028x; 1.0028x over previous
; __device__ __forceinline__ void norm_phase(ArgP a, LAS unsigned char* lds, int l, bool final_, const int tid, const int bid) {
;     ...
;     for (int row = bid * NWAVES + wave; row < SEQ; row += gridDim.x * NWAVES) {
.LBB0_527:
	s_or_b64 exec, exec, s[4:5]
	s_add_i32 s2, s2, s88
	s_cmpk_lt_i32 s2, 0x4000
	s_cbranch_scc0 .LBB0_530
	s_waitcnt vmcnt(1) lgkmcnt(0)
	s_branch .Lrow_top

; __device__ __forceinline__ void norm_phase(ArgP a, LAS unsigned char* lds, int l, bool final_, const int tid, const int bid) {
;     ...
;     for (int row = bid * NWAVES + wave; row < SEQ; row += gridDim.x * NWAVES) {
;         const f32x4* xr = (const f32x4*)(xsrc + (size_t)row * DM);
;         f32x4 v[8]; float ss = 0.f;
; #pragma unroll
;         for (int j = 0; j < 8; ++j) { v[j] = xr[64 * j + lane]; ss += (v[j][0] * v[j][0] + v[j][1] * v[j][1]) + (v[j][2] * v[j][2] + v[j][3] * v[j][3]); }
.Lrow_top:
	v_mov_b64_e32 v[44:45], v[82:83]
	v_mov_b64_e32 v[46:47], v[84:85]
	v_mov_b64_e32 v[24:25], v[86:87]
	v_mov_b64_e32 v[26:27], v[88:89]
	v_mov_b64_e32 v[20:21], v[90:91]
	v_mov_b64_e32 v[22:23], v[92:93]
	v_mov_b64_e32 v[16:17], v[94:95]
	v_mov_b64_e32 v[18:19], v[96:97]
	v_mov_b64_e32 v[12:13], v[98:99]
	v_mov_b64_e32 v[14:15], v[100:101]
	v_mov_b64_e32 v[8:9], v[102:103]
	v_mov_b64_e32 v[10:11], v[104:105]
	v_mov_b64_e32 v[4:5], v[106:107]
	v_mov_b64_e32 v[6:7], v[108:109]
	v_mov_b64_e32 v[0:1], v[110:111]
	v_mov_b64_e32 v[2:3], v[112:113]
	s_add_i32 s3, s2, s88
	s_cmpk_lt_i32 s3, 0x4000
	s_cbranch_scc0 .Lrow_nopf
	s_mov_b32 s4, s3
	s_ashr_i32 s5, s4, 31
	s_lshl_b64 s[4:5], s[4:5], 13
	s_add_u32 s4, s0, s4
	s_addc_u32 s5, s1, s5
	global_load_dwordx4 v[82:85], v39, s[4:5]
	global_load_dwordx4 v[86:89], v39, s[4:5] offset:1024
	global_load_dwordx4 v[90:93], v39, s[4:5] offset:2048
	global_load_dwordx4 v[94:97], v39, s[4:5] offset:3072
	global_load_dwordx4 v[98:101], v40, s[4:5]
	global_load_dwordx4 v[102:105], v41, s[4:5]
	global_load_dwordx4 v[106:109], v42, s[4:5]
	global_load_dwordx4 v[110:113], v43, s[4:5]
